# top-k rank loop with 64-bit (value,index) keys; gates and first K/V blocks of the selected and window branches loaded early
# speedup vs baseline: 1.0152x; 1.0042x over previous
; template <int MODE  > ...
;     ...
;     kreg = *(const u32x4*)(Kg + (size_t)(64 * j + skey) * 128 + schunk * 8);
;     if (NEEDV) vreg = *(const u32x4*)(Vg + (size_t)(64 * j + skey) * 128 + schunk * 8);
; __device__ __forceinline__ void attn_unit(unsigned char* ws, LAS unsigned char* lds, int b, int g, int c, const int tid) {
;     const int lane = tid & 63, w = tid >> 6, col = lane & 31, h = lane >> 5, r = col >> 3, qi = col & 7;
;     const int q = 8 * w + qi, t = 64 * c + q, head = g * 4 + r;
;     const size_t row = (size_t)b * SEQ + t;
;     const float slope2 = exp2f(-(float)(head + 1)) * LOG2E;
;     const bf16_t* Qp = (const bf16_t*)(ws + WS_Q) + row * 512 + head * 64 + 8 * h;
;     bf16x8 qf[4];
; #pragma unroll
;     for (int kk = 0; kk < 4; ++kk) qf[kk] = *(const bf16x8*)(Qp + 16 * kk);
;     ...
;     { const float gate0 = ((const float*)(ws + WS_G))[row * 32 + head * 3 + 0]; const float sc = st.l > 0.f ? gate0 / st.l : 0.f;
.LBB0_142:
	s_and_b32 s68, s14, 7
	v_lshl_add_u32 v188, s83, 6, v198
	s_lshl_b32 s62, s68, 12
	v_ashrrev_i32_e32 v189, 31, v188
	v_lshl_add_u64 v[184:185], s[62:63], 0, v[188:189]
	v_lshl_or_b32 v210, s16, 2, v196
	v_lshlrev_b64 v[2:3], 10, v[184:185]
	v_lshl_add_u64 v[2:3], s[38:39], 0, v[2:3]
	v_lshlrev_b32_e32 v4, 7, v210
	v_mov_b32_e32 v5, v0
	v_lshl_add_u64 v[2:3], v[2:3], 0, v[4:5]
	v_lshl_add_u64 v[2:3], v[2:3], 0, v[180:181]
	global_load_dwordx4 v[144:147], v[2:3], off
	global_load_dwordx4 v[148:151], v[2:3], off offset:32
	global_load_dwordx4 v[152:155], v[2:3], off offset:64
	global_load_dwordx4 v[156:159], v[2:3], off offset:96
	v_lshlrev_b64 v[252:253], 5, v[184:185]
	v_mul_u32_u24_e32 v254, 3, v210
	v_or_b32_e32 v252, v252, v254
	v_lshl_add_u64 v[252:253], v[252:253], 2, s[92:93]
	global_load_dword v245, v[252:253], off
	global_load_dword v246, v[252:253], off offset:4
	global_load_dword v247, v[252:253], off offset:8
	s_lshl_b32 s4, s68, 19
	s_lshl_b32 s5, s16, 6
	s_or_b32 s4, s4, s5
	s_lshl_b32 s4, s4, 1
	s_add_u32 s14, s45, s4
	s_addc_u32 s15, s46, 0
	s_add_u32 s18, s43, s4
	s_addc_u32 s19, s44, 0
	v_ashrrev_i32_e32 v224, 3, v178
	v_lshl_add_u32 v224, s83, 6, v224
	v_ashrrev_i32_e32 v225, 31, v224
	v_lshlrev_b64 v[224:225], 8, v[224:225]
	v_lshlrev_b32_e32 v254, 4, v178
	v_and_b32_e32 v254, 0x70, v254
	v_or_b32_e32 v224, v224, v254
	v_lshl_add_u64 v[252:253], s[14:15], 0, v[224:225]
	global_load_dwordx4 v[220:223], v[252:253], off
	v_lshl_add_u64 v[252:253], s[18:19], 0, v[224:225]
	global_load_dwordx4 v[248:251], v[252:253], off
	s_and_saveexec_b64 s[4:5], s[8:9]
	s_cbranch_execz .LBB0_145
	s_mov_b64 s[14:15], 0
	v_mov_b32_e32 v1, v207
	v_mov_b32_e32 v2, v206

; __device__ __forceinline__ void attn_unit(unsigned char* ws, LAS unsigned char* lds, int b, int g, int c, const int tid) {
;     ...
;     { const float gate0 = ((const float*)(ws + WS_G))[row * 32 + head * 3 + 0]; const float sc = st.l > 0.f ? gate0 / st.l : 0.f;
.LBB0_159:
	v_lshlrev_b64 v[4:5], 5, v[184:185]
	v_mul_u32_u24_e32 v2, 3, v210
	v_or_b32_e32 v4, v4, v2
	v_mov_b32_e32 v2, 0
	v_cmp_lt_f32_e64 s[16:17], 0, v3
	v_lshl_add_u64 v[138:139], v[4:5], 2, s[92:93]
	s_and_saveexec_b64 s[14:15], s[16:17]
	s_cbranch_execz .LBB0_161
	v_mov_b32_e32 v2, v245
	s_waitcnt vmcnt(0) lgkmcnt(0)
	v_div_scale_f32 v4, s[20:21], v3, v3, v2
	v_rcp_f32_e32 v5, v4
	v_div_scale_f32 v6, vcc, v2, v3, v2
	v_fma_f32 v7, -v4, v5, 1.0
	v_fmac_f32_e32 v5, v7, v5
	v_mul_f32_e32 v7, v6, v5
	v_fma_f32 v8, -v4, v7, v6
	v_fmac_f32_e32 v7, v8, v5
	v_fma_f32 v4, -v4, v7, v6
	v_div_fmas_f32 v4, v4, v5, v7
	v_div_fixup_f32 v2, v4, v3, v2

; __device__ __forceinline__ void attn_unit(unsigned char* ws, LAS unsigned char* lds, int b, int g, int c, const int tid) {
;     ...
;             const int qq = tidk >> 3, jg = tidk & 7;
;             float mine[8]; int rank[8];
; #pragma unroll
;             for (int e = 0; e < 8; ++e) { mine[e] = impA[qq * IMPP + 8 * jg + e]; rank[e] = 0; }
;             for (int jp = 1; jp <= c - 2; ++jp) {
;                 const float v = impA[qq * IMPP + jp];
; #pragma unroll
;                 for (int e = 0; e < 8; ++e) { const int jm = 8 * jg + e; rank[e] += (v > mine[e] || (v == mine[e] && jp < jm)) ? 1 : 0; }
;             }
.LBB0_200:
	s_or_b64 exec, exec, s[4:5]
	v_ashrrev_i32_e32 v1, 3, v39
	v_and_b32_e32 v42, 7, v39
	s_movk_i32 s4, 0x104
	v_mul_lo_u32 v43, v1, s4
	v_lshlrev_b32_e32 v1, 5, v42
	v_add3_u32 v1, 0, v43, v1
	v_add_u32_e32 v2, 0xa800, v1
	s_waitcnt lgkmcnt(0)
	s_barrier
	v_add_u32_e32 v3, 0xa808, v1
	v_add_u32_e32 v4, 0xa810, v1
	v_add_u32_e32 v1, 0xa818, v1
	ds_read2_b32 v[16:17], v2 offset1:1
	ds_read2_b32 v[18:19], v3 offset1:1
	ds_read2_b32 v[20:21], v4 offset1:1
	ds_read2_b32 v[22:23], v1 offset1:1
	s_add_i32 s69, s83, -2
	v_lshlrev_b32_e32 v14, 3, v42
	v_or_b32_e32 v12, 2, v14
	v_or_b32_e32 v10, 3, v14
	v_or_b32_e32 v8, 4, v14
	v_or_b32_e32 v6, 5, v14
	v_or_b32_e32 v4, 6, v14
	s_cmp_lt_u32 s69, 2
	v_or_b32_e32 v2, 7, v14
	s_cbranch_scc1 .LBB0_206
	s_waitcnt vmcnt(0) lgkmcnt(0)
	v_not_b32_e32 v100, v14
	v_mov_b32_e32 v101, v16
	v_or_b32_e32 v102, 1, v14
	v_not_b32_e32 v102, v102
	v_mov_b32_e32 v103, v17
	v_not_b32_e32 v104, v12
	v_mov_b32_e32 v105, v18
	v_not_b32_e32 v106, v10
	v_mov_b32_e32 v107, v19
	v_not_b32_e32 v108, v8
	v_mov_b32_e32 v109, v20
	v_not_b32_e32 v110, v6
	v_mov_b32_e32 v111, v21
	v_not_b32_e32 v112, v4
	v_mov_b32_e32 v113, v22
	v_not_b32_e32 v114, v2
	v_mov_b32_e32 v115, v23
	v_mov_b32_e32 v15, 0
	v_mov_b32_e32 v13, 0
	v_mov_b32_e32 v11, 0
	v_mov_b32_e32 v9, 0
	v_mov_b32_e32 v7, 0
	v_mov_b32_e32 v5, 0
	v_mov_b32_e32 v3, 0
	v_mov_b32_e32 v1, 0
	v_readlane_b32 s5, v255, 11
	s_mov_b32 s84, 1
	s_nop 1
	v_add_u32_e32 v60, s5, v43
	ds_read2_b32 v[120:121], v60 offset1:1
.Ltk_loop:
	s_add_i32 s5, s84, 1
	s_not_b32 s4, s84
	s_cmp_le_u32 s5, s69
	s_cselect_b32 s22, -1, 0
	s_not_b32 s5, s5
	s_and_b32 s5, s5, s22
	v_mov_b32_e32 v116, s4
	v_mov_b32_e32 v118, s5
	v_add_u32_e32 v60, 8, v60
	s_waitcnt lgkmcnt(0)
	v_mov_b32_e32 v117, v120
	v_and_b32_e32 v119, s22, v121
	ds_read2_b32 v[120:121], v60 offset1:1
	v_cmp_gt_u64_e64 s[14:15], v[116:117], v[100:101]
	v_cmp_gt_u64_e64 s[16:17], v[116:117], v[102:103]
	v_cmp_gt_u64_e64 s[18:19], v[116:117], v[104:105]
	v_cmp_gt_u64_e64 s[20:21], v[116:117], v[106:107]
	v_addc_co_u32_e64 v15, vcc, 0, v15, s[14:15]
	v_addc_co_u32_e64 v13, vcc, 0, v13, s[16:17]
	v_addc_co_u32_e64 v11, vcc, 0, v11, s[18:19]
	v_addc_co_u32_e64 v9, vcc, 0, v9, s[20:21]
	v_cmp_gt_u64_e64 s[14:15], v[116:117], v[108:109]
	v_cmp_gt_u64_e64 s[16:17], v[116:117], v[110:111]
	v_cmp_gt_u64_e64 s[18:19], v[116:117], v[112:113]
	v_cmp_gt_u64_e64 s[20:21], v[116:117], v[114:115]
	v_addc_co_u32_e64 v7, vcc, 0, v7, s[14:15]
	v_addc_co_u32_e64 v5, vcc, 0, v5, s[16:17]
	v_addc_co_u32_e64 v3, vcc, 0, v3, s[18:19]
	v_addc_co_u32_e64 v1, vcc, 0, v1, s[20:21]
	v_cmp_gt_u64_e64 s[14:15], v[118:119], v[100:101]
	v_cmp_gt_u64_e64 s[16:17], v[118:119], v[102:103]
	v_cmp_gt_u64_e64 s[18:19], v[118:119], v[104:105]
	v_cmp_gt_u64_e64 s[20:21], v[118:119], v[106:107]
	v_addc_co_u32_e64 v15, vcc, 0, v15, s[14:15]
	v_addc_co_u32_e64 v13, vcc, 0, v13, s[16:17]
	v_addc_co_u32_e64 v11, vcc, 0, v11, s[18:19]
	v_addc_co_u32_e64 v9, vcc, 0, v9, s[20:21]
	v_cmp_gt_u64_e64 s[14:15], v[118:119], v[108:109]
	v_cmp_gt_u64_e64 s[16:17], v[118:119], v[110:111]
	v_cmp_gt_u64_e64 s[18:19], v[118:119], v[112:113]
	v_cmp_gt_u64_e64 s[20:21], v[118:119], v[114:115]
	v_addc_co_u32_e64 v7, vcc, 0, v7, s[14:15]
	v_addc_co_u32_e64 v5, vcc, 0, v5, s[16:17]
	v_addc_co_u32_e64 v3, vcc, 0, v3, s[18:19]
	v_addc_co_u32_e64 v1, vcc, 0, v1, s[20:21]
	s_add_i32 s84, s84, 2
	s_cmp_le_u32 s84, s69
	s_cbranch_scc1 .Ltk_loop
	s_waitcnt lgkmcnt(0)
	s_add_i32 s4, s83, -1
	v_mov_b32_e32 v24, s4
	s_branch .LBB0_210

; #define LAS __attribute__((address_space(3)))
; template <int MODE  > ...
;     int lane = lane_in, tid = tid_in;
;     asm volatile("" : "+v"(lane), "+v"(tid));
;     constexpr bool NEEDV = (MODE != 3);
;     constexpr bool CMPM = (MODE == 0 || MODE == 3);
;     const int col = lane & 31, h = lane >> 5;
;     const int skey = tid >> 3, schunk = tid & 7;
;     unsigned long long rem = blockmask;
;     if (!rem) return;
;     int j = 63 - __builtin_clzll(rem); rem &= ~(1ull << j);
;     u32x4 kreg, vreg;
;     kreg = *(const u32x4*)(Kg + (size_t)(64 * j + skey) * 128 + schunk * 8);
;     if (NEEDV) vreg = *(const u32x4*)(Vg + (size_t)(64 * j + skey) * 128 + schunk * 8);
;     int cur = 0;
;     {
;         LAS bf16_t* kb = (LAS bf16_t*)(lds + A_KBUF) + cur * 64 * KPITCH;
;         *(LAS u32x4*)(kb + skey * KPITCH + schunk * 8) = kreg;
;         if (NEEDV) { LAS bf16_t* vb = (LAS bf16_t*)(lds + A_VBUF) + cur * 64 * VPITCH;
;             *(LAS u32x4*)(vb + skey * VPITCH + schunk * 8) = vreg; }
;     }
;     __syncthreads();
;     for (;;) {
;         const bool has_next = rem != 0ull; int jn = 0;
;         if (has_next) { jn = 63 - __builtin_clzll(rem); rem &= ~(1ull << jn);
;             kreg = *(const u32x4*)(Kg + (size_t)(64 * jn + skey) * 128 + schunk * 8);
;             if (NEEDV) vreg = *(const u32x4*)(Vg + (size_t)(64 * jn + skey) * 128 + schunk * 8); }
.LBB0_246:
	s_lshl_b32 s4, s68, 19
	s_or_b32 s22, s62, s4
	v_mov_b32_e32 v1, v179
	v_mov_b32_e32 v2, v178
	s_cmp_eq_u64 s[14:15], 0
	v_add_f32_e32 v187, v186, v186
	s_waitcnt vmcnt(0)
	v_fma_f32 v163, 2.0, v186, v186
	s_cbranch_scc1 .LBB0_263
	s_lshl_b32 s16, s22, 1
	s_add_u32 s4, s43, s16
	s_addc_u32 s5, s44, 0
	s_add_u32 s16, s45, s16
	s_flbit_i32_b64 s18, s[14:15]
	v_ashrrev_i32_e32 v164, 3, v2
	s_addc_u32 s17, s46, 0
	s_xor_b32 s68, s18, 63
	v_lshl_add_u32 v4, s68, 6, v164
	v_ashrrev_i32_e32 v5, 31, v4
	v_lshlrev_b64 v[4:5], 8, v[4:5]
	v_lshlrev_b32_e32 v2, 4, v2
	v_lshl_add_u64 v[6:7], s[16:17], 0, v[4:5]
	v_and_b32_e32 v16, 0x70, v2
	v_mov_b32_e32 v17, v0
	v_lshl_add_u64 v[2:3], v[6:7], 0, v[16:17]
	v_lshl_add_u64 v[4:5], s[4:5], 0, v[4:5]
	v_lshl_add_u64 v[4:5], v[4:5], 0, v[16:17]
	v_ashrrev_i32_e32 v18, 5, v1
	v_lshrrev_b32_e32 v34, 2, v1
	v_lshlrev_b32_e32 v37, 2, v18
	v_and_or_b32 v34, v34, 3, v37
	v_and_b32_e32 v19, 31, v1
	v_and_b32_e32 v21, 16, v1
	v_lshlrev_b32_e32 v22, 3, v1
	s_movk_i32 s18, 0x90
	v_mul_lo_u32 v34, v34, s70
	v_lshlrev_b32_e32 v20, 2, v1
	v_mov_b32_e32 v14, v0
	v_mov_b32_e32 v15, v0
	v_mul_lo_u32 v35, v164, s18
	v_mul_lo_u32 v36, v164, s70
	v_mul_u32_u24_e32 v38, 0x90, v19
	v_lshlrev_b32_e32 v39, 1, v21
	v_and_b32_e32 v40, 24, v22
	v_lshlrev_b32_e32 v41, 4, v18
	v_add_u32_e32 v34, 0, v34
	v_mov_b32_e32 v1, v0
	v_mov_b32_e32 v2, v0
	v_mov_b32_e32 v3, v0
	v_mov_b32_e32 v4, v0
	v_mov_b32_e32 v5, v0
	v_mov_b32_e32 v6, v0
	v_mov_b32_e32 v7, v0
	v_mov_b32_e32 v8, v0
	v_mov_b32_e32 v9, v0
	v_mov_b32_e32 v10, v0
	v_mov_b32_e32 v11, v0
	v_mov_b32_e32 v12, v0
	v_mov_b32_e32 v13, v0
	v_bitop3_b32 v165, v20, s66, v240 bitop3:0x6c
	v_mov_b64_e32 v[32:33], v[14:15]
	v_add3_u32 v166, 0, v35, v16
	v_add3_u32 v167, 0, v36, v16
	v_sub_u32_e32 v190, v37, v188
	v_add3_u32 v191, 0, v38, v41
	v_lshl_add_u64 v[142:143], s[4:5], 0, v[16:17]
	s_lshl_b64 s[4:5], 1, s68
	v_add3_u32 v192, v34, v39, v40
	v_mov_b64_e32 v[48:49], v[14:15]
	s_mov_b32 s23, 0
	v_mov_b32_e32 v194, 0xefa18f08
	v_mov_b32_e32 v193, 0
	v_mov_b64_e32 v[30:31], v[12:13]
	v_mov_b64_e32 v[28:29], v[10:11]
	v_mov_b64_e32 v[26:27], v[8:9]
	v_mov_b64_e32 v[24:25], v[6:7]
	v_mov_b64_e32 v[22:23], v[4:5]
	v_mov_b64_e32 v[20:21], v[2:3]
	v_mov_b64_e32 v[18:19], v[0:1]
	v_lshl_add_u64 v[160:161], s[16:17], 0, v[16:17]
	s_andn2_b64 s[14:15], s[14:15], s[4:5]
	v_mov_b64_e32 v[46:47], v[12:13]
	v_mov_b64_e32 v[44:45], v[10:11]
	v_mov_b64_e32 v[42:43], v[8:9]
	v_mov_b64_e32 v[40:41], v[6:7]
	v_mov_b64_e32 v[38:39], v[4:5]
	v_mov_b64_e32 v[36:37], v[2:3]
	v_mov_b64_e32 v[34:35], v[0:1]
	s_mov_b64 s[18:19], s[14:15]
	s_mov_b32 s20, 0
	s_cmp_eq_u64 s[18:19], 0
	s_cbranch_scc1 .Lm1_pre_nob1
	s_flbit_i32_b64 s62, s[18:19]
	s_xor_b32 s62, s62, 63
	s_lshl_b64 s[4:5], 1, s62
	s_andn2_b64 s[18:19], s[18:19], s[4:5]
	v_lshl_add_u32 v2, s62, 6, v164
	v_ashrrev_i32_e32 v3, 31, v2
	v_lshlrev_b64 v[2:3], 8, v[2:3]
	v_lshl_add_u64 v[4:5], v[160:161], 0, v[2:3]
	v_lshl_add_u64 v[2:3], v[142:143], 0, v[2:3]
	global_load_dwordx4 v[226:229], v[4:5], off
	global_load_dwordx4 v[230:233], v[2:3], off
	s_mov_b32 s20, 1
	s_waitcnt vmcnt(2)
	s_branch .Lm1_pre_w

; #define LAS __attribute__((address_space(3)))
; template <int MODE  > ...
;     ...
;     kreg = *(const u32x4*)(Kg + (size_t)(64 * j + skey) * 128 + schunk * 8);
;     if (NEEDV) vreg = *(const u32x4*)(Vg + (size_t)(64 * j + skey) * 128 + schunk * 8);
;     int cur = 0;
;     {
;         LAS bf16_t* kb = (LAS bf16_t*)(lds + A_KBUF) + cur * 64 * KPITCH;
;         *(LAS u32x4*)(kb + skey * KPITCH + schunk * 8) = kreg;
;         if (NEEDV) { LAS bf16_t* vb = (LAS bf16_t*)(lds + A_VBUF) + cur * 64 * VPITCH;
;             *(LAS u32x4*)(vb + skey * VPITCH + schunk * 8) = vreg; }
;     }
;     __syncthreads();
;     for (;;) {
;         const bool has_next = rem != 0ull; int jn = 0;
;         if (has_next) { jn = 63 - __builtin_clzll(rem); rem &= ~(1ull << jn);
;             kreg = *(const u32x4*)(Kg + (size_t)(64 * jn + skey) * 128 + schunk * 8);
;             if (NEEDV) vreg = *(const u32x4*)(Vg + (size_t)(64 * jn + skey) * 128 + schunk * 8); }
; __device__ __forceinline__ void attn_unit(unsigned char* ws, LAS unsigned char* lds, int b, int g, int c, const int tid) {
;     ...
;       attn_pass<2>(lds, (const bf16_t*)(ws + WS_KW) + boff, (const bf16_t*)(ws + WS_VW) + boff, winmask, qf, st, t, slope2, 0ull, w, lane, tid, c); }
.Lm1_pre_w:
	s_waitcnt lgkmcnt(0)
	ds_write_b128 v166, v[220:223]
	ds_write_b128 v167, v[248:251] offset:18432
	s_waitcnt lgkmcnt(0)
	s_barrier
	s_lshl_b32 s4, s22, 1
	s_add_u32 s14, s49, s4
	s_addc_u32 s15, s82, 0
	s_add_u32 s4, s47, s4
	s_addc_u32 s5, s48, 0
	v_lshl_add_u32 v2, s83, 6, v164
	v_ashrrev_i32_e32 v3, 31, v2
	v_lshlrev_b64 v[2:3], 8, v[2:3]
	v_lshlrev_b32_e32 v4, 4, v178
	v_and_b32_e32 v4, 0x70, v4
	v_or_b32_e32 v2, v2, v4
	v_lshl_add_u64 v[4:5], s[14:15], 0, v[2:3]
	global_load_dwordx4 v[220:223], v[4:5], off
	v_lshl_add_u64 v[4:5], s[4:5], 0, v[2:3]
	global_load_dwordx4 v[248:251], v[4:5], off
.LBB0_248:
	s_mov_b32 s21, 0
	s_cmp_eq_u64 s[18:19], 0
	s_cbranch_scc1 .Lm1_noload
	s_flbit_i32_b64 s4, s[18:19]
	s_xor_b32 s4, s4, 63
	s_lshl_b64 vcc, 1, s4
	s_andn2_b64 s[18:19], s[18:19], vcc
	s_mov_b32 s21, 1
	v_lshl_add_u32 v2, s4, 6, v164
	v_ashrrev_i32_e32 v3, 31, v2
	v_lshlrev_b64 v[2:3], 8, v[2:3]
	v_lshl_add_u64 v[4:5], v[160:161], 0, v[2:3]
	v_lshl_add_u64 v[2:3], v[142:143], 0, v[2:3]
	s_cmp_eq_u32 s23, 0
	s_cbranch_scc0 .Lm1_loadB
	global_load_dwordx4 v[130:133], v[4:5], off
	global_load_dwordx4 v[134:137], v[2:3], off
	s_branch .Lm1_noload

; #define LAS __attribute__((address_space(3)))
; template <int MODE  > ...
;     ...
;         const bool selbit = (MODE == 1) ? (((selmask >> j) & 1ull) != 0ull) : true;
;         bool active = true;
;         if (MODE == 1) active = __builtin_amdgcn_ballot_w64(selbit) != 0ull;
;         if (active) {
;             const LAS bf16_t* kb = (const LAS bf16_t*)(lds + A_KBUF) + cur * 64 * KPITCH;
;             constexpr int STEP = CMPM ? 16 : 1;
;             const int Bint = CMPM ? (1024 * j + 31 - t + 64 * h) : (64 * j - t + 4 * h);
;             const float sl = slope2 * (float)STEP;
;             const float mref = st.m; const bool fresh = !(mref > -1e28f);
;             const float mest = fresh ? 0.f : mref;
;             const float basef = selbit ? (slope2 * (float)Bint - mest) : -1e30f;
;             int ptype;
;             if (MODE == 1) ptype = (j == cblk) ? 1 : 0;
;             else if (MODE == 2) ptype = (j == cblk) ? 1 : ((j == cblk - 8) ? 2 : 0);
;             else ptype = (64 * j + 63 <= 4 * cblk - 2) ? 0 : 1;
;             f32x16 s0, s1;
;             { const float sl2 = sl + sl, sl3 = sl2 + sl;
; #pragma unroll
;               for (int g8 = 0; g8 < 4; ++g8) {
;                   const float b0 = __builtin_fmaf(sl, (float)(8 * g8), basef), b1 = __builtin_fmaf(sl, (float)(8 * g8 + 32), basef);
;                   s0[4 * g8] = b0; s0[4 * g8 + 1] = b0 + sl; s0[4 * g8 + 2] = b0 + sl2; s0[4 * g8 + 3] = b0 + sl3;
;                   s1[4 * g8] = b1; s1[4 * g8 + 1] = b1 + sl; s1[4 * g8 + 2] = b1 + sl2; s1[4 * g8 + 3] = b1 + sl3;
;               } }
;             if (ptype == 1) {
;                 const float thr = 0.5f * slope2 - mest;
; #pragma unroll
;                 for (int i = 0; i < 16; ++i) { s0[i] = (s0[i] < thr) ? s0[i] : -1e30f; s1[i] = (s1[i] < thr) ? s1[i] : -1e30f; }
;             } else if (ptype == 2) {
;                 const float thr = -511.5f * slope2 - mest;
; #pragma unroll
;                 for (int i = 0; i < 16; ++i) { s0[i] = (s0[i] > thr) ? s0[i] : -1e30f; s1[i] = (s1[i] > thr) ? s1[i] : -1e30f; }
;             }
; #pragma unroll
;             for (int kk = 0; kk < 4; ++kk) {
;                 const bf16x8 k0 = *(const LAS bf16x8*)(kb + col * KPITCH + kk * 16 + h * 8);
;                 const bf16x8 k1 = *(const LAS bf16x8*)(kb + (32 + col) * KPITCH + kk * 16 + h * 8);
.Lm1_noload:
.LBB0_250:
	v_lshrrev_b64 v[2:3], s68, v[140:141]
	v_and_b32_e32 v1, 1, v2
	v_cmp_eq_u32_e64 s[16:17], 1, v1
	v_cmp_ne_u32_e32 vcc, 0, v1
	s_cbranch_vccz .LBB0_258
	s_mul_i32 vcc_lo, s23, 0x2400
	s_mul_i32 vcc_hi, s23, 0x3000
	v_add_u32_e32 v254, vcc_lo, v191
	v_add_u32_e32 v225, vcc_hi, v192
	ds_read_b128 v[66:69], v254
	ds_read_b128 v[70:73], v254 offset:4608
	ds_read_b128 v[74:77], v254 offset:32
	ds_read_b128 v[78:81], v254 offset:4640
	ds_read_b128 v[82:85], v254 offset:64
	ds_read_b128 v[86:89], v254 offset:4672
	ds_read_b128 v[90:93], v254 offset:96
	ds_read_b128 v[94:97], v254 offset:4704
	v_lshl_add_u32 v1, s68, 6, v190
	v_cvt_f32_i32_e32 v2, v1
	v_cmp_nlt_f32_e64 s[14:15], s71, v194
	s_cmp_lg_u32 s68, s83
	s_nop 0
	v_cndmask_b32_e64 v1, v194, 0, s[14:15]
	v_fma_f32 v2, v186, v2, -v1
	v_cndmask_b32_e64 v14, v241, v2, s[16:17]
	v_fma_f32 v50, 0, v186, v14
	v_fmamk_f32 v54, v186, 0x41000000, v14
	v_fmamk_f32 v58, v186, 0x41800000, v14
	v_fmamk_f32 v62, v186, 0x41c00000, v14
	v_fmamk_f32 v2, v186, 0x42000000, v14
	v_fmamk_f32 v6, v186, 0x42200000, v14
	v_fmamk_f32 v10, v186, 0x42400000, v14
	v_fmac_f32_e32 v14, 0x42600000, v186
	v_add_f32_e32 v51, v186, v50
	v_add_f32_e32 v52, v187, v50
	v_add_f32_e32 v53, v163, v50
	v_add_f32_e32 v55, v186, v54
	v_add_f32_e32 v56, v187, v54
	v_add_f32_e32 v57, v163, v54
	v_add_f32_e32 v59, v186, v58
	v_add_f32_e32 v60, v187, v58
	v_add_f32_e32 v61, v163, v58
	v_add_f32_e32 v63, v186, v62
	v_add_f32_e32 v64, v187, v62
	v_add_f32_e32 v65, v163, v62
	v_add_f32_e32 v3, v186, v2
	v_add_f32_e32 v4, v187, v2
	v_add_f32_e32 v5, v163, v2
	v_add_f32_e32 v7, v186, v6
	v_add_f32_e32 v8, v187, v6
	v_add_f32_e32 v9, v163, v6
	v_add_f32_e32 v11, v186, v10
	v_add_f32_e32 v12, v187, v10
	v_add_f32_e32 v13, v163, v10
	v_add_f32_e32 v15, v186, v14
	v_add_f32_e32 v16, v187, v14
	v_add_f32_e32 v17, v163, v14
	s_cbranch_scc1 .Lm1_qk
	v_sub_f32_e32 v253, v189, v1
	v_cmp_lt_f32_e32 vcc, v50, v253
	s_nop 1
	v_cndmask_b32_e32 v50, v241, v50, vcc
	v_cmp_lt_f32_e32 vcc, v51, v253
	s_nop 1
	v_cndmask_b32_e32 v51, v241, v51, vcc
	v_cmp_lt_f32_e32 vcc, v52, v253
	s_nop 1
	v_cndmask_b32_e32 v52, v241, v52, vcc
	v_cmp_lt_f32_e32 vcc, v53, v253
	s_nop 1
	v_cndmask_b32_e32 v53, v241, v53, vcc
	v_cmp_lt_f32_e32 vcc, v54, v253
	s_nop 1
	v_cndmask_b32_e32 v54, v241, v54, vcc
	v_cmp_lt_f32_e32 vcc, v55, v253
	s_nop 1
	v_cndmask_b32_e32 v55, v241, v55, vcc
	v_cmp_lt_f32_e32 vcc, v56, v253
	s_nop 1
	v_cndmask_b32_e32 v56, v241, v56, vcc
	v_cmp_lt_f32_e32 vcc, v57, v253
	s_nop 1
	v_cndmask_b32_e32 v57, v241, v57, vcc
	v_cmp_lt_f32_e32 vcc, v58, v253
	s_nop 1
	v_cndmask_b32_e32 v58, v241, v58, vcc
	v_cmp_lt_f32_e32 vcc, v59, v253
	s_nop 1
	v_cndmask_b32_e32 v59, v241, v59, vcc
	v_cmp_lt_f32_e32 vcc, v60, v253
	s_nop 1
	v_cndmask_b32_e32 v60, v241, v60, vcc
	v_cmp_lt_f32_e32 vcc, v61, v253
	s_nop 1
	v_cndmask_b32_e32 v61, v241, v61, vcc
	v_cmp_lt_f32_e32 vcc, v62, v253
	s_nop 1
	v_cndmask_b32_e32 v62, v241, v62, vcc
	v_cmp_lt_f32_e32 vcc, v63, v253
	s_nop 1
	v_cndmask_b32_e32 v63, v241, v63, vcc
	v_cmp_lt_f32_e32 vcc, v64, v253
	s_nop 1
	v_cndmask_b32_e32 v64, v241, v64, vcc
	v_cmp_lt_f32_e32 vcc, v65, v253
	s_nop 1
	v_cndmask_b32_e32 v65, v241, v65, vcc
	v_cmp_lt_f32_e32 vcc, v2, v253
	s_nop 1
	v_cndmask_b32_e32 v2, v241, v2, vcc
	v_cmp_lt_f32_e32 vcc, v3, v253
	s_nop 1
	v_cndmask_b32_e32 v3, v241, v3, vcc
	v_cmp_lt_f32_e32 vcc, v4, v253
	s_nop 1
	v_cndmask_b32_e32 v4, v241, v4, vcc
	v_cmp_lt_f32_e32 vcc, v5, v253
	s_nop 1
	v_cndmask_b32_e32 v5, v241, v5, vcc
	v_cmp_lt_f32_e32 vcc, v6, v253
	s_nop 1
	v_cndmask_b32_e32 v6, v241, v6, vcc
	v_cmp_lt_f32_e32 vcc, v7, v253
	s_nop 1
	v_cndmask_b32_e32 v7, v241, v7, vcc
	v_cmp_lt_f32_e32 vcc, v8, v253
	s_nop 1
	v_cndmask_b32_e32 v8, v241, v8, vcc
	v_cmp_lt_f32_e32 vcc, v9, v253
	s_nop 1
	v_cndmask_b32_e32 v9, v241, v9, vcc
	v_cmp_lt_f32_e32 vcc, v10, v253
	s_nop 1
	v_cndmask_b32_e32 v10, v241, v10, vcc
	v_cmp_lt_f32_e32 vcc, v11, v253
	s_nop 1
	v_cndmask_b32_e32 v11, v241, v11, vcc
	v_cmp_lt_f32_e32 vcc, v12, v253
	s_nop 1
	v_cndmask_b32_e32 v12, v241, v12, vcc
	v_cmp_lt_f32_e32 vcc, v13, v253
	s_nop 1
	v_cndmask_b32_e32 v13, v241, v13, vcc
	v_cmp_lt_f32_e32 vcc, v14, v253
	s_nop 1
	v_cndmask_b32_e32 v14, v241, v14, vcc
	v_cmp_lt_f32_e32 vcc, v15, v253
	s_nop 1
	v_cndmask_b32_e32 v15, v241, v15, vcc
	v_cmp_lt_f32_e32 vcc, v16, v253
	s_nop 1
	v_cndmask_b32_e32 v16, v241, v16, vcc
	v_cmp_lt_f32_e32 vcc, v17, v253
	s_nop 1
	v_cndmask_b32_e32 v17, v241, v17, vcc
; template <int MODE  > ...
;     ...
;             for (int kk = 0; kk < 4; ++kk) {
;                 const bf16x8 k0 = *(const LAS bf16x8*)(kb + col * KPITCH + kk * 16 + h * 8);
;                 const bf16x8 k1 = *(const LAS bf16x8*)(kb + (32 + col) * KPITCH + kk * 16 + h * 8);
;                 s0 = __builtin_amdgcn_mfma_f32_32x32x16_bf16(k0, qf[kk], s0, 0, 0, 0);
;                 s1 = __builtin_amdgcn_mfma_f32_32x32x16_bf16(k1, qf[kk], s1, 0, 0, 0);
;             }
;             if (MODE != 3) {
;                 float mx = fmaxf(s0[0], s1[0]);
; #pragma unroll
;                 for (int i = 1; i < 16; ++i) mx = fmaxf(mx, fmaxf(s0[i], s1[i]));
;                 mx = fmaxf(mx, shflx(mx, 32, lane));
;                 float alpha = 1.f;
;                 if (__builtin_amdgcn_ballot_w64(fresh || mx > 0.f) != 0ull) {
;                     const float moldr = fresh ? -1e29f : 0.f, mnewr = fmaxf(moldr, mx);
;                     alpha = __builtin_amdgcn_exp2f(moldr - mnewr);
;                     st.m = mest + mnewr;
; #pragma unroll
;                     for (int i = 0; i < 16; ++i) { s0[i] = __builtin_amdgcn_exp2f(s0[i] - mnewr); s1[i] = __builtin_amdgcn_exp2f(s1[i] - mnewr); }
;                     st.o0 *= alpha; st.o1 *= alpha;
;                 } else {
; #pragma unroll
;                     for (int i = 0; i < 16; ++i) { s0[i] = __builtin_amdgcn_exp2f(s0[i]); s1[i] = __builtin_amdgcn_exp2f(s1[i]); }
;                 }
;                 { typedef float f32x8 __attribute__((ext_vector_type(8)));
;                   const f32x16 t16 = s0 + s1;
;                   const f32x8 t8 = __builtin_shufflevector(t16, t16, 0, 1, 2, 3, 4, 5, 6, 7) + __builtin_shufflevector(t16, t16, 8, 9, 10, 11, 12, 13, 14, 15);
;                   const f32x4 t4 = __builtin_shufflevector(t8, t8, 0, 1, 2, 3) + __builtin_shufflevector(t8, t8, 4, 5, 6, 7);
;                   float ps = (t4[0] + t4[1]) + (t4[2] + t4[3]);
;                   ps += shflx(ps, 32, lane);
;                   st.l = st.l * alpha + ps; }
;                 bf16x8 pf[4];
; #pragma unroll
;                 for (int kk = 0; kk < 4; ++kk) {
;                     u32x4 pw;
;                     if (kk < 2) { pw.x = pk2(s0[8 * kk], s0[8 * kk + 1]); pw.y = pk2(s0[8 * kk + 2], s0[8 * kk + 3]); pw.z = pk2(s0[8 * kk + 4], s0[8 * kk + 5]); pw.w = pk2(s0[8 * kk + 6], s0[8 * kk + 7]); }
.Lm1_qk:
	s_waitcnt lgkmcnt(7)
	v_mfma_f32_32x32x16_bf16 v[50:65], v[66:69], v[144:147], v[50:65]
	s_waitcnt lgkmcnt(6)
	v_mfma_f32_32x32x16_bf16 v[2:17], v[70:73], v[144:147], v[2:17]
	s_waitcnt lgkmcnt(5)
	v_mfma_f32_32x32x16_bf16 v[50:65], v[74:77], v[148:151], v[50:65]
	s_waitcnt lgkmcnt(4)
	v_mfma_f32_32x32x16_bf16 v[2:17], v[78:81], v[148:151], v[2:17]
	s_waitcnt lgkmcnt(3)
	v_mfma_f32_32x32x16_bf16 v[50:65], v[82:85], v[152:155], v[50:65]
	s_waitcnt lgkmcnt(2)
	v_mfma_f32_32x32x16_bf16 v[2:17], v[86:89], v[152:155], v[2:17]
	s_waitcnt lgkmcnt(1)
	v_mfma_f32_32x32x16_bf16 v[50:65], v[90:93], v[156:159], v[50:65]
	s_waitcnt lgkmcnt(0)
	v_mfma_f32_32x32x16_bf16 v[2:17], v[94:97], v[156:159], v[2:17]
	ds_read_b64_tr_b16 v[66:67], v225 offset:18432
	ds_read_b64_tr_b16 v[68:69], v225 offset:19968
	ds_read_b64_tr_b16 v[70:71], v225 offset:18496
	ds_read_b64_tr_b16 v[72:73], v225 offset:20032
	ds_read_b64_tr_b16 v[74:75], v225 offset:21504
	ds_read_b64_tr_b16 v[76:77], v225 offset:23040
	ds_read_b64_tr_b16 v[78:79], v225 offset:21568
	ds_read_b64_tr_b16 v[80:81], v225 offset:23104
	s_nop 3
	v_max3_f32 v234, v50, v51, v52
	v_max3_f32 v234, v234, v53, v54
	v_max3_f32 v234, v234, v55, v56
	v_max3_f32 v234, v234, v57, v58
	v_max3_f32 v234, v234, v59, v60
	v_max3_f32 v234, v234, v61, v62
	v_max3_f32 v234, v234, v63, v64
	v_max3_f32 v235, v2, v3, v4
	v_max3_f32 v235, v235, v5, v6
	v_max3_f32 v235, v235, v7, v8
	v_max3_f32 v235, v235, v9, v10
	v_max3_f32 v235, v235, v11, v12
	v_max3_f32 v235, v235, v13, v14
	v_max3_f32 v235, v235, v15, v16
	v_max3_f32 v234, v234, v65, v17
	v_max_f32_e32 v234, v234, v235
	ds_bpermute_b32 v235, v165, v234
	ds_read_b64_tr_b16 v[82:83], v225 offset:24576
	ds_read_b64_tr_b16 v[84:85], v225 offset:26112
	ds_read_b64_tr_b16 v[86:87], v225 offset:24640
	ds_read_b64_tr_b16 v[88:89], v225 offset:26176
	ds_read_b64_tr_b16 v[90:91], v225 offset:27648
	ds_read_b64_tr_b16 v[92:93], v225 offset:29184
	ds_read_b64_tr_b16 v[94:95], v225 offset:27712
	ds_read_b64_tr_b16 v[96:97], v225 offset:29248
	s_waitcnt lgkmcnt(8)
	v_max_f32_e32 v234, v234, v235
	v_cmp_lt_f32_e32 vcc, 0, v234
	s_or_b64 vcc, s[14:15], vcc
	s_cbranch_vccz .Lm1_norescale
	v_cndmask_b32_e64 v235, 0, v242, s[14:15]
	v_max_f32_e32 v234, v235, v234
	v_sub_f32_e32 v235, v235, v234
	v_exp_f32_e32 v162, v235
	v_add_f32_e32 v194, v1, v234
	v_sub_f32_e32 v114, v50, v234
	v_exp_f32_e32 v114, v114
	v_sub_f32_e32 v98, v2, v234
	v_exp_f32_e32 v98, v98
	v_sub_f32_e32 v115, v51, v234
	v_exp_f32_e32 v115, v115
	v_sub_f32_e32 v99, v3, v234
	v_exp_f32_e32 v99, v99
	v_sub_f32_e32 v116, v52, v234
	v_exp_f32_e32 v116, v116
	v_sub_f32_e32 v100, v4, v234
	v_exp_f32_e32 v100, v100
	v_sub_f32_e32 v117, v53, v234
	v_exp_f32_e32 v117, v117
	v_sub_f32_e32 v101, v5, v234
	v_exp_f32_e32 v101, v101
	v_sub_f32_e32 v118, v54, v234
	v_exp_f32_e32 v118, v118
	v_sub_f32_e32 v102, v6, v234
	v_exp_f32_e32 v102, v102
	v_sub_f32_e32 v119, v55, v234
	v_exp_f32_e32 v119, v119
	v_sub_f32_e32 v103, v7, v234
	v_exp_f32_e32 v103, v103
	v_sub_f32_e32 v120, v56, v234
	v_exp_f32_e32 v120, v120
	v_sub_f32_e32 v104, v8, v234
	v_exp_f32_e32 v104, v104
	v_sub_f32_e32 v121, v57, v234
	v_exp_f32_e32 v121, v121
	v_sub_f32_e32 v105, v9, v234
	v_exp_f32_e32 v105, v105
	v_sub_f32_e32 v122, v58, v234
	v_exp_f32_e32 v122, v122
	v_sub_f32_e32 v106, v10, v234
	v_exp_f32_e32 v106, v106
	v_sub_f32_e32 v123, v59, v234
	v_exp_f32_e32 v123, v123
	v_sub_f32_e32 v107, v11, v234
	v_exp_f32_e32 v107, v107
	v_sub_f32_e32 v124, v60, v234
	v_exp_f32_e32 v124, v124
	v_sub_f32_e32 v108, v12, v234
	v_exp_f32_e32 v108, v108
	v_sub_f32_e32 v125, v61, v234
	v_exp_f32_e32 v125, v125
	v_sub_f32_e32 v109, v13, v234
	v_exp_f32_e32 v109, v109
	v_sub_f32_e32 v126, v62, v234
	v_exp_f32_e32 v126, v126
	v_sub_f32_e32 v110, v14, v234
	v_exp_f32_e32 v110, v110
	v_sub_f32_e32 v127, v63, v234
	v_exp_f32_e32 v127, v127
	v_sub_f32_e32 v111, v15, v234
	v_exp_f32_e32 v111, v111
	v_sub_f32_e32 v128, v64, v234
	v_exp_f32_e32 v128, v128
	v_sub_f32_e32 v112, v16, v234
	v_exp_f32_e32 v112, v112
	v_sub_f32_e32 v129, v65, v234
	v_exp_f32_e32 v129, v129
	v_sub_f32_e32 v113, v17, v234
	v_exp_f32_e32 v113, v113
	v_pk_mul_f32 v[18:19], v[18:19], v[162:163] op_sel_hi:[1,0]
	v_pk_mul_f32 v[20:21], v[20:21], v[162:163] op_sel_hi:[1,0]
	v_pk_mul_f32 v[22:23], v[22:23], v[162:163] op_sel_hi:[1,0]
	v_pk_mul_f32 v[24:25], v[24:25], v[162:163] op_sel_hi:[1,0]
	v_pk_mul_f32 v[26:27], v[26:27], v[162:163] op_sel_hi:[1,0]
	v_pk_mul_f32 v[28:29], v[28:29], v[162:163] op_sel_hi:[1,0]
	v_pk_mul_f32 v[30:31], v[30:31], v[162:163] op_sel_hi:[1,0]
	v_pk_mul_f32 v[32:33], v[32:33], v[162:163] op_sel_hi:[1,0]
	v_pk_mul_f32 v[34:35], v[34:35], v[162:163] op_sel_hi:[1,0]
	v_pk_mul_f32 v[36:37], v[36:37], v[162:163] op_sel_hi:[1,0]
	v_pk_mul_f32 v[38:39], v[38:39], v[162:163] op_sel_hi:[1,0]
	v_pk_mul_f32 v[40:41], v[40:41], v[162:163] op_sel_hi:[1,0]
	v_pk_mul_f32 v[42:43], v[42:43], v[162:163] op_sel_hi:[1,0]
	v_pk_mul_f32 v[44:45], v[44:45], v[162:163] op_sel_hi:[1,0]
	v_pk_mul_f32 v[46:47], v[46:47], v[162:163] op_sel_hi:[1,0]
	v_pk_mul_f32 v[48:49], v[48:49], v[162:163] op_sel_hi:[1,0]
	s_branch .Lm1_pv

; #define LAS __attribute__((address_space(3)))
; template <int MODE  > ...
;     ...
;         if (has_next) {
;             LAS bf16_t* kb = (LAS bf16_t*)(lds + A_KBUF) + (cur ^ 1) * 64 * KPITCH;
;             *(LAS u32x4*)(kb + skey * KPITCH + schunk * 8) = kreg;
;             if (NEEDV) { LAS bf16_t* vb = (LAS bf16_t*)(lds + A_VBUF) + (cur ^ 1) * 64 * VPITCH;
;                 *(LAS u32x4*)(vb + skey * VPITCH + schunk * 8) = vreg; }
.LBB0_258:
	s_cmp_eq_u32 s20, 0
	s_cbranch_scc1 .LBB0_260
	s_lshl_b32 s14, s23, 6
	s_xor_b32 s14, s14, 64
	s_mul_i32 s15, s14, 0x90
	v_add_u32_e32 v2, s15, v166
	s_mulk_i32 s14, 0xc0
	v_add_u32_e32 v3, s14, v167
	s_cmp_eq_u32 s21, 0
	s_cbranch_scc1 .Lm1_w0
	s_waitcnt vmcnt(2)
	s_branch .Lm1_w1

; #define LAS __attribute__((address_space(3)))
; template <int MODE  > ...
;     ...
;         if (has_next) {
;             LAS bf16_t* kb = (LAS bf16_t*)(lds + A_KBUF) + (cur ^ 1) * 64 * KPITCH;
;             *(LAS u32x4*)(kb + skey * KPITCH + schunk * 8) = kreg;
;             if (NEEDV) { LAS bf16_t* vb = (LAS bf16_t*)(lds + A_VBUF) + (cur ^ 1) * 64 * VPITCH;
;                 *(LAS u32x4*)(vb + skey * VPITCH + schunk * 8) = vreg; }
.Lm1_w1:
	s_cmp_eq_u32 s23, 0
	s_cbranch_scc0 .Lm1_stA
	ds_write_b128 v2, v[226:229]
	ds_write_b128 v3, v[230:233] offset:18432
	s_branch .LBB0_260
.Lm1_stA:
	ds_write_b128 v2, v[130:133]
	ds_write_b128 v3, v[134:137] offset:18432

; __device__ __forceinline__ void attn_unit(unsigned char* ws, LAS unsigned char* lds, int b, int g, int c, const int tid) {
;     ...
;     { const float gate1 = ((const float*)(ws + WS_G))[row * 32 + head * 3 + 1]; const float sc = st.l > 0.f ? gate1 / st.l : 0.f;
; #pragma unroll
;       for (int i = 0; i < 16; ++i) { outl[i * 512] += st.o0[i] * sc; outl[(16 + i) * 512] += st.o1[i] * sc; } }
.LBB0_264:
	v_mov_b32_e32 v17, 0
	v_cmp_lt_f32_e32 vcc, 0, v193
	v_mov_b32_e32 v1, 0
	s_and_saveexec_b64 s[4:5], vcc
	s_cbranch_execz .LBB0_266
	v_mov_b32_e32 v1, v246
	s_waitcnt vmcnt(0) lgkmcnt(0)
	v_div_scale_f32 v2, s[14:15], v193, v193, v1
	v_rcp_f32_e32 v3, v2
	v_div_scale_f32 v4, vcc, v1, v193, v1
	v_fma_f32 v5, -v2, v3, 1.0
	v_fmac_f32_e32 v3, v5, v3
	v_mul_f32_e32 v5, v4, v3
	v_fma_f32 v6, -v2, v5, v4
	v_fmac_f32_e32 v5, v6, v3
	v_fma_f32 v2, -v2, v5, v4
	v_div_fmas_f32 v2, v2, v3, v5
	v_div_fixup_f32 v1, v2, v193, v1
; #define LAS __attribute__((address_space(3)))
; template <int MODE  > ...
;     ...
;     unsigned long long rem = blockmask;
;     if (!rem) return;
;     int j = 63 - __builtin_clzll(rem); rem &= ~(1ull << j);
;     u32x4 kreg, vreg;
;     kreg = *(const u32x4*)(Kg + (size_t)(64 * j + skey) * 128 + schunk * 8);
;     if (NEEDV) vreg = *(const u32x4*)(Vg + (size_t)(64 * j + skey) * 128 + schunk * 8);
;     int cur = 0;
;     {
;         LAS bf16_t* kb = (LAS bf16_t*)(lds + A_KBUF) + cur * 64 * KPITCH;
;         *(LAS u32x4*)(kb + skey * KPITCH + schunk * 8) = kreg;
;         if (NEEDV) { LAS bf16_t* vb = (LAS bf16_t*)(lds + A_VBUF) + cur * 64 * VPITCH;
;             *(LAS u32x4*)(vb + skey * VPITCH + schunk * 8) = vreg; }
;     }
;     __syncthreads();
;     for (;;) {
;         const bool has_next = rem != 0ull; int jn = 0;
;         if (has_next) { jn = 63 - __builtin_clzll(rem); rem &= ~(1ull << jn);
;             kreg = *(const u32x4*)(Kg + (size_t)(64 * jn + skey) * 128 + schunk * 8);
;             if (NEEDV) vreg = *(const u32x4*)(Vg + (size_t)(64 * jn + skey) * 128 + schunk * 8); }
; __device__ __forceinline__ void attn_unit(unsigned char* ws, LAS unsigned char* lds, int b, int g, int c, const int tid) {
;     ...
;       for (int i = 0; i < 16; ++i) { outl[i * 512] += st.o0[i] * sc; outl[(16 + i) * 512] += st.o1[i] * sc; } }
;     st.m = -1e29f; st.l = 0.f; st.o0 = (f32x16){}; st.o1 = (f32x16){};
;     { const int jlo = c >= 8 ? c - 8 : 0; const unsigned long long upto = (c >= 63) ? ~0ull : ((1ull << (c + 1)) - 1ull);
;       const unsigned long long winmask = upto & ~((1ull << jlo) - 1ull);
;       attn_pass<2>(lds, (const bf16_t*)(ws + WS_KW) + boff, (const bf16_t*)(ws + WS_VW) + boff, winmask, qf, st, t, slope2, 0ull, w, lane, tid, c); }
.LBB0_266:
	s_or_b64 exec, exec, s[4:5]
	ds_read2st64_b32 v[2:3], v199 offset1:8
	ds_read2st64_b32 v[4:5], v199 offset0:128 offset1:136
	s_add_i32 s4, s83, 1
	s_lshl_b64 s[4:5], -1, s4
	s_not_b64 s[4:5], s[4:5]
	s_waitcnt lgkmcnt(0)
	v_fma_f32 v2, v18, v1, v2
	v_fma_f32 v4, v34, v1, v4
	v_fmac_f32_e32 v3, v19, v1
	v_fmac_f32_e32 v5, v35, v1
	ds_write2st64_b32 v199, v2, v3 offset1:8
	ds_write2st64_b32 v199, v4, v5 offset0:128 offset1:136
	ds_read2st64_b32 v[2:3], v199 offset0:16 offset1:24
	ds_read2st64_b32 v[4:5], v199 offset0:144 offset1:152
	s_cmp_lt_u32 s83, 63
	s_cselect_b32 s5, s5, -1
	s_cselect_b32 s4, s4, -1
	s_waitcnt lgkmcnt(0)
	v_fma_f32 v2, v20, v1, v2
	v_fma_f32 v4, v36, v1, v4
	v_fmac_f32_e32 v3, v21, v1
	v_fmac_f32_e32 v5, v37, v1
	ds_write2st64_b32 v199, v2, v3 offset0:16 offset1:24
	ds_write2st64_b32 v199, v4, v5 offset0:144 offset1:152
	ds_read2st64_b32 v[2:3], v199 offset0:32 offset1:40
	ds_read2st64_b32 v[4:5], v199 offset0:160 offset1:168
	v_mov_b32_e32 v34, v178
	v_mov_b32_e32 v16, 0
	v_mov_b32_e32 v15, 0
	s_waitcnt lgkmcnt(0)
	v_fma_f32 v2, v22, v1, v2
	v_fma_f32 v4, v38, v1, v4
	v_fmac_f32_e32 v3, v23, v1
	v_fmac_f32_e32 v5, v39, v1
	ds_write2st64_b32 v199, v2, v3 offset0:32 offset1:40
	ds_write2st64_b32 v199, v4, v5 offset0:160 offset1:168
	ds_read2st64_b32 v[2:3], v199 offset0:48 offset1:56
	ds_read2st64_b32 v[4:5], v199 offset0:176 offset1:184
	v_mov_b32_e32 v14, 0
	v_mov_b32_e32 v13, 0
	v_mov_b32_e32 v12, 0
	s_waitcnt lgkmcnt(0)
	v_fma_f32 v2, v24, v1, v2
	v_fma_f32 v4, v40, v1, v4
	v_fmac_f32_e32 v3, v25, v1
	v_fmac_f32_e32 v5, v41, v1
	ds_write2st64_b32 v199, v2, v3 offset0:48 offset1:56
	ds_write2st64_b32 v199, v4, v5 offset0:176 offset1:184
	ds_read2st64_b32 v[2:3], v199 offset0:64 offset1:72
	ds_read2st64_b32 v[4:5], v199 offset0:192 offset1:200
	v_mov_b32_e32 v11, 0
	v_mov_b32_e32 v10, 0
	v_mov_b32_e32 v9, 0
	s_waitcnt lgkmcnt(0)
	v_fma_f32 v2, v26, v1, v2
	v_fma_f32 v4, v42, v1, v4
	v_fmac_f32_e32 v3, v27, v1
	v_fmac_f32_e32 v5, v43, v1
	ds_write2st64_b32 v199, v2, v3 offset0:64 offset1:72
	ds_write2st64_b32 v199, v4, v5 offset0:192 offset1:200
	ds_read2st64_b32 v[2:3], v199 offset0:80 offset1:88
	ds_read2st64_b32 v[4:5], v199 offset0:208 offset1:216
	v_mov_b32_e32 v8, 0
	v_mov_b32_e32 v7, 0
	v_mov_b32_e32 v6, 0
	s_waitcnt lgkmcnt(0)
	v_fma_f32 v2, v28, v1, v2
	v_fma_f32 v4, v44, v1, v4
	v_fmac_f32_e32 v3, v29, v1
	v_fmac_f32_e32 v5, v45, v1
	ds_write2st64_b32 v199, v2, v3 offset0:80 offset1:88
	ds_write2st64_b32 v199, v4, v5 offset0:208 offset1:216
	ds_read2st64_b32 v[2:3], v199 offset0:96 offset1:104
	ds_read2st64_b32 v[4:5], v199 offset0:224 offset1:232
	v_mov_b32_e32 v29, 0
	v_mov_b32_e32 v28, 0
	v_mov_b32_e32 v27, 0
	s_waitcnt lgkmcnt(0)
	v_fma_f32 v2, v30, v1, v2
	v_fma_f32 v4, v46, v1, v4
	v_fmac_f32_e32 v3, v31, v1
	v_fmac_f32_e32 v5, v47, v1
	ds_write2st64_b32 v199, v2, v3 offset0:96 offset1:104
	ds_write2st64_b32 v199, v4, v5 offset0:224 offset1:232
	ds_read2st64_b32 v[2:3], v199 offset0:112 offset1:120
	ds_read2st64_b32 v[4:5], v199 offset0:240 offset1:248
	v_mov_b32_e32 v31, 0
	v_mov_b32_e32 v30, 0
	v_mov_b32_e32 v26, 0
	s_waitcnt lgkmcnt(0)
	v_fma_f32 v2, v32, v1, v2
	v_fma_f32 v4, v48, v1, v4
	v_fmac_f32_e32 v3, v33, v1
	v_fmac_f32_e32 v5, v49, v1
	v_sub_u32_e64 v1, s83, 8 clamp
	ds_write2st64_b32 v199, v2, v3 offset0:112 offset1:120
	v_readfirstlane_b32 s14, v1
	s_lshl_b64 s[14:15], -1, s14
	s_and_b64 s[4:5], s[4:5], s[14:15]
	ds_write2st64_b32 v199, v4, v5 offset0:240 offset1:248
	v_mov_b32_e32 v1, v179
	s_cmp_eq_u64 s[4:5], 0
	v_mov_b32_e32 v5, 0
	v_mov_b32_e32 v4, 0
	v_mov_b32_e32 v3, 0
	v_mov_b32_e32 v2, 0
	v_mov_b32_e32 v33, 0
	v_mov_b32_e32 v32, 0
	v_mov_b32_e32 v25, 0
	v_mov_b32_e32 v24, 0
	v_mov_b32_e32 v23, 0
	v_mov_b32_e32 v22, 0
	v_mov_b32_e32 v21, 0
	v_mov_b32_e32 v20, 0
	v_mov_b32_e32 v19, 0
	v_mov_b32_e32 v18, 0
	v_mov_b32_e32 v35, 0
	s_cbranch_scc1 .LBB0_285
	s_lshl_b32 s16, s22, 1
	s_add_u32 s14, s47, s16
	s_addc_u32 s15, s48, 0
	s_add_u32 s16, s49, s16
	s_flbit_i32_b64 s18, s[4:5]
	v_ashrrev_i32_e32 v161, 3, v34
	s_addc_u32 s17, s82, 0
	s_xor_b32 s20, s18, 63
	v_lshl_add_u32 v2, s20, 6, v161
	v_ashrrev_i32_e32 v3, 31, v2
	v_lshlrev_b64 v[2:3], 8, v[2:3]
	v_lshlrev_b32_e32 v6, 4, v34
	v_lshl_add_u64 v[4:5], s[16:17], 0, v[2:3]
	v_and_b32_e32 v16, 0x70, v6
	v_mov_b32_e32 v17, v0
	v_lshl_add_u64 v[4:5], v[4:5], 0, v[16:17]
	v_lshl_add_u64 v[2:3], s[14:15], 0, v[2:3]
	v_lshl_add_u64 v[2:3], v[2:3], 0, v[16:17]
	s_waitcnt vmcnt(0)
	v_ashrrev_i32_e32 v18, 5, v1
	v_lshrrev_b32_e32 v34, 2, v1
	v_lshlrev_b32_e32 v37, 2, v18
	v_and_b32_e32 v19, 31, v1
	v_lshlrev_b32_e32 v20, 2, v1
	v_and_b32_e32 v21, 16, v1
	v_lshlrev_b32_e32 v22, 3, v1
	v_mov_b32_e32 v14, v0
	v_mov_b32_e32 v15, v0
	s_movk_i32 s18, 0x90
	v_and_or_b32 v34, v34, 3, v37
	v_mov_b32_e32 v1, v0
	v_mov_b32_e32 v2, v0
	v_mov_b32_e32 v3, v0
	v_mov_b32_e32 v4, v0
	v_mov_b32_e32 v5, v0
	v_mov_b32_e32 v6, v0
	v_mov_b32_e32 v7, v0
	v_mov_b32_e32 v8, v0
	v_mov_b32_e32 v9, v0
	v_mov_b32_e32 v10, v0
	v_mov_b32_e32 v11, v0
	v_mov_b32_e32 v12, v0
	v_mov_b32_e32 v13, v0
	v_mul_lo_u32 v35, v161, s18
	v_mul_lo_u32 v36, v161, s70
	v_mul_u32_u24_e32 v38, 0x90, v19
	v_bitop3_b32 v164, v20, s66, v240 bitop3:0x6c
	v_lshlrev_b32_e32 v39, 1, v21
	v_and_b32_e32 v40, 24, v22
	v_lshlrev_b32_e32 v41, 4, v18
	v_mov_b64_e32 v[32:33], v[14:15]
	v_mul_lo_u32 v34, v34, s70
	v_mov_b64_e32 v[30:31], v[12:13]
	v_mov_b64_e32 v[28:29], v[10:11]
	v_mov_b64_e32 v[26:27], v[8:9]
	v_mov_b64_e32 v[24:25], v[6:7]
	v_mov_b64_e32 v[22:23], v[4:5]
	v_mov_b64_e32 v[20:21], v[2:3]
	v_mov_b64_e32 v[18:19], v[0:1]
	v_add3_u32 v165, 0, v35, v16
	v_add3_u32 v166, 0, v36, v16
	v_lshl_add_u64 v[140:141], s[14:15], 0, v[16:17]
	v_add_u32_e32 v34, 0, v34
	s_lshl_b64 s[14:15], 1, s20
	v_lshl_add_u64 v[142:143], s[16:17], 0, v[16:17]
	v_mov_b64_e32 v[16:17], v[14:15]
	v_mul_f32_e32 v162, 0xc3ffc000, v186
	s_mov_b32 s22, 0
	v_mov_b32_e32 v192, 0xefa18f08
	v_mov_b32_e32 v190, 0
	v_sub_u32_e32 v167, v37, v188
	v_add3_u32 v188, 0, v38, v41
	s_add_i32 s23, s83, -8
	v_add3_u32 v191, v34, v39, v40
	s_andn2_b64 s[14:15], s[4:5], s[14:15]
	v_mov_b64_e32 v[14:15], v[12:13]
	v_mov_b64_e32 v[12:13], v[10:11]
	v_mov_b64_e32 v[10:11], v[8:9]
	v_mov_b64_e32 v[8:9], v[6:7]
	v_mov_b64_e32 v[6:7], v[4:5]
	v_mov_b64_e32 v[4:5], v[2:3]
	v_mov_b64_e32 v[2:3], v[0:1]
	s_mov_b64 s[16:17], s[14:15]
	s_mov_b32 s18, 0
	s_cmp_eq_u64 s[16:17], 0
	s_cbranch_scc1 .Lm2_pre_nob1
	s_flbit_i32_b64 s62, s[16:17]
	s_xor_b32 s62, s62, 63
	s_lshl_b64 s[4:5], 1, s62
	s_andn2_b64 s[16:17], s[16:17], s[4:5]
	v_lshl_add_u32 v34, s62, 6, v161
	v_ashrrev_i32_e32 v35, 31, v34
	v_lshlrev_b64 v[34:35], 8, v[34:35]
	v_lshl_add_u64 v[36:37], v[142:143], 0, v[34:35]
	v_lshl_add_u64 v[34:35], v[140:141], 0, v[34:35]
	global_load_dwordx4 v[226:229], v[36:37], off
	global_load_dwordx4 v[230:233], v[34:35], off
	s_mov_b32 s18, 1
	s_waitcnt vmcnt(2)
	s_branch .Lm2_pre_w

; #define LAS __attribute__((address_space(3)))
; template <int MODE  > ...
;     ...
;     {
;         LAS bf16_t* kb = (LAS bf16_t*)(lds + A_KBUF) + cur * 64 * KPITCH;
;         *(LAS u32x4*)(kb + skey * KPITCH + schunk * 8) = kreg;
;         if (NEEDV) { LAS bf16_t* vb = (LAS bf16_t*)(lds + A_VBUF) + cur * 64 * VPITCH;
;             *(LAS u32x4*)(vb + skey * VPITCH + schunk * 8) = vreg; }
;     }
;     __syncthreads();
.Lm2_pre_w:
	s_waitcnt lgkmcnt(0)
	ds_write_b128 v165, v[220:223]
	ds_write_b128 v166, v[248:251] offset:18432
	s_waitcnt lgkmcnt(0)
	s_barrier

; #define LAS __attribute__((address_space(3)))
; template <int MODE  > ...
;     ...
;             const LAS bf16_t* kb = (const LAS bf16_t*)(lds + A_KBUF) + cur * 64 * KPITCH;
;             constexpr int STEP = CMPM ? 16 : 1;
;             const int Bint = CMPM ? (1024 * j + 31 - t + 64 * h) : (64 * j - t + 4 * h);
;             const float sl = slope2 * (float)STEP;
;             const float mref = st.m; const bool fresh = !(mref > -1e28f);
;             const float mest = fresh ? 0.f : mref;
;             const float basef = selbit ? (slope2 * (float)Bint - mest) : -1e30f;
;             int ptype;
;             if (MODE == 1) ptype = (j == cblk) ? 1 : 0;
;             else if (MODE == 2) ptype = (j == cblk) ? 1 : ((j == cblk - 8) ? 2 : 0);
;             else ptype = (64 * j + 63 <= 4 * cblk - 2) ? 0 : 1;
;             f32x16 s0, s1;
;             { const float sl2 = sl + sl, sl3 = sl2 + sl;
; #pragma unroll
;               for (int g8 = 0; g8 < 4; ++g8) {
;                   const float b0 = __builtin_fmaf(sl, (float)(8 * g8), basef), b1 = __builtin_fmaf(sl, (float)(8 * g8 + 32), basef);
;                   s0[4 * g8] = b0; s0[4 * g8 + 1] = b0 + sl; s0[4 * g8 + 2] = b0 + sl2; s0[4 * g8 + 3] = b0 + sl3;
;                   s1[4 * g8] = b1; s1[4 * g8 + 1] = b1 + sl; s1[4 * g8 + 2] = b1 + sl2; s1[4 * g8 + 3] = b1 + sl3;
;               } }
;             if (ptype == 1) {
;                 const float thr = 0.5f * slope2 - mest;
; #pragma unroll
;                 for (int i = 0; i < 16; ++i) { s0[i] = (s0[i] < thr) ? s0[i] : -1e30f; s1[i] = (s1[i] < thr) ? s1[i] : -1e30f; }
;             } else if (ptype == 2) {
;                 const float thr = -511.5f * slope2 - mest;
; #pragma unroll
;                 for (int i = 0; i < 16; ++i) { s0[i] = (s0[i] > thr) ? s0[i] : -1e30f; s1[i] = (s1[i] > thr) ? s1[i] : -1e30f; }
;             }
.Lm2_noload:
.Lm2_body:
	s_mul_i32 vcc_lo, s22, 0x2400
	s_mul_i32 vcc_hi, s22, 0x3000
	v_add_u32_e32 v254, vcc_lo, v188
	v_add_u32_e32 v225, vcc_hi, v191
	ds_read_b128 v[66:69], v254
	ds_read_b128 v[70:73], v254 offset:4608
	ds_read_b128 v[74:77], v254 offset:32
	ds_read_b128 v[78:81], v254 offset:4640
	ds_read_b128 v[82:85], v254 offset:64
	ds_read_b128 v[86:89], v254 offset:4672
	ds_read_b128 v[90:93], v254 offset:96
	ds_read_b128 v[94:97], v254 offset:4704
	v_lshl_add_u32 v1, s20, 6, v167
	v_cvt_f32_i32_e32 v50, v1
	v_cmp_nlt_f32_e64 s[14:15], s71, v192
	s_cmp_eq_u32 s20, s23
	s_cselect_b32 s21, 2, 0
	s_cmp_lg_u32 s20, s83
	s_cselect_b32 s68, s21, 1
	s_cmp_eq_u32 s68, 0
	v_cndmask_b32_e64 v1, v192, 0, s[14:15]
	v_fma_f32 v62, v186, v50, -v1
	v_fma_f32 v34, 0, v186, v62
	v_fmamk_f32 v38, v186, 0x41000000, v62
	v_fmamk_f32 v42, v186, 0x41800000, v62
	v_fmamk_f32 v46, v186, 0x41c00000, v62
	v_fmamk_f32 v50, v186, 0x42000000, v62
	v_fmamk_f32 v54, v186, 0x42200000, v62
	v_fmamk_f32 v58, v186, 0x42400000, v62
	v_fmac_f32_e32 v62, 0x42600000, v186
	v_add_f32_e32 v35, v186, v34
	v_add_f32_e32 v36, v187, v34
	v_add_f32_e32 v37, v163, v34
	v_add_f32_e32 v39, v186, v38
	v_add_f32_e32 v40, v187, v38
	v_add_f32_e32 v41, v163, v38
	v_add_f32_e32 v43, v186, v42
	v_add_f32_e32 v44, v187, v42
	v_add_f32_e32 v45, v163, v42
	v_add_f32_e32 v47, v186, v46
	v_add_f32_e32 v48, v187, v46
	v_add_f32_e32 v49, v163, v46
	v_add_f32_e32 v51, v186, v50
	v_add_f32_e32 v52, v187, v50
	v_add_f32_e32 v53, v163, v50
	v_add_f32_e32 v55, v186, v54
	v_add_f32_e32 v56, v187, v54
	v_add_f32_e32 v57, v163, v54
	v_add_f32_e32 v59, v186, v58
	v_add_f32_e32 v60, v187, v58
	v_add_f32_e32 v61, v163, v58
	v_add_f32_e32 v63, v186, v62
	v_add_f32_e32 v64, v187, v62
	v_add_f32_e32 v65, v163, v62
	s_cbranch_scc1 .Lm2_qk
	s_cmp_eq_u32 s68, 1
	s_cbranch_scc1 .Lm2_edge1
	v_sub_f32_e32 v253, v162, v1
	v_cmp_gt_f32_e32 vcc, v34, v253
	s_nop 1
	v_cndmask_b32_e32 v34, v241, v34, vcc
	v_cmp_gt_f32_e32 vcc, v35, v253
	s_nop 1
	v_cndmask_b32_e32 v35, v241, v35, vcc
	v_cmp_gt_f32_e32 vcc, v36, v253
	s_nop 1
	v_cndmask_b32_e32 v36, v241, v36, vcc
	v_cmp_gt_f32_e32 vcc, v37, v253
	s_nop 1
	v_cndmask_b32_e32 v37, v241, v37, vcc
	v_cmp_gt_f32_e32 vcc, v38, v253
	s_nop 1
	v_cndmask_b32_e32 v38, v241, v38, vcc
	v_cmp_gt_f32_e32 vcc, v39, v253
	s_nop 1
	v_cndmask_b32_e32 v39, v241, v39, vcc
	v_cmp_gt_f32_e32 vcc, v40, v253
	s_nop 1
	v_cndmask_b32_e32 v40, v241, v40, vcc
	v_cmp_gt_f32_e32 vcc, v41, v253
	s_nop 1
	v_cndmask_b32_e32 v41, v241, v41, vcc
	v_cmp_gt_f32_e32 vcc, v42, v253
	s_nop 1
	v_cndmask_b32_e32 v42, v241, v42, vcc
	v_cmp_gt_f32_e32 vcc, v43, v253
	s_nop 1
	v_cndmask_b32_e32 v43, v241, v43, vcc
	v_cmp_gt_f32_e32 vcc, v44, v253
	s_nop 1
	v_cndmask_b32_e32 v44, v241, v44, vcc
	v_cmp_gt_f32_e32 vcc, v45, v253
	s_nop 1
	v_cndmask_b32_e32 v45, v241, v45, vcc
	v_cmp_gt_f32_e32 vcc, v46, v253
	s_nop 1
	v_cndmask_b32_e32 v46, v241, v46, vcc
	v_cmp_gt_f32_e32 vcc, v47, v253
	s_nop 1
	v_cndmask_b32_e32 v47, v241, v47, vcc
	v_cmp_gt_f32_e32 vcc, v48, v253
	s_nop 1
	v_cndmask_b32_e32 v48, v241, v48, vcc
	v_cmp_gt_f32_e32 vcc, v49, v253
	s_nop 1
	v_cndmask_b32_e32 v49, v241, v49, vcc
	v_cmp_gt_f32_e32 vcc, v50, v253
	s_nop 1
	v_cndmask_b32_e32 v50, v241, v50, vcc
	v_cmp_gt_f32_e32 vcc, v51, v253
	s_nop 1
	v_cndmask_b32_e32 v51, v241, v51, vcc
	v_cmp_gt_f32_e32 vcc, v52, v253
	s_nop 1
	v_cndmask_b32_e32 v52, v241, v52, vcc
	v_cmp_gt_f32_e32 vcc, v53, v253
	s_nop 1
	v_cndmask_b32_e32 v53, v241, v53, vcc
	v_cmp_gt_f32_e32 vcc, v54, v253
	s_nop 1
	v_cndmask_b32_e32 v54, v241, v54, vcc
	v_cmp_gt_f32_e32 vcc, v55, v253
	s_nop 1
	v_cndmask_b32_e32 v55, v241, v55, vcc
	v_cmp_gt_f32_e32 vcc, v56, v253
	s_nop 1
	v_cndmask_b32_e32 v56, v241, v56, vcc
	v_cmp_gt_f32_e32 vcc, v57, v253
	s_nop 1
	v_cndmask_b32_e32 v57, v241, v57, vcc
	v_cmp_gt_f32_e32 vcc, v58, v253
	s_nop 1
	v_cndmask_b32_e32 v58, v241, v58, vcc
	v_cmp_gt_f32_e32 vcc, v59, v253
	s_nop 1
	v_cndmask_b32_e32 v59, v241, v59, vcc
	v_cmp_gt_f32_e32 vcc, v60, v253
	s_nop 1
	v_cndmask_b32_e32 v60, v241, v60, vcc
	v_cmp_gt_f32_e32 vcc, v61, v253
	s_nop 1
	v_cndmask_b32_e32 v61, v241, v61, vcc
	v_cmp_gt_f32_e32 vcc, v62, v253
	s_nop 1
	v_cndmask_b32_e32 v62, v241, v62, vcc
	v_cmp_gt_f32_e32 vcc, v63, v253
	s_nop 1
	v_cndmask_b32_e32 v63, v241, v63, vcc
	v_cmp_gt_f32_e32 vcc, v64, v253
	s_nop 1
	v_cndmask_b32_e32 v64, v241, v64, vcc
	v_cmp_gt_f32_e32 vcc, v65, v253
	s_nop 1
	v_cndmask_b32_e32 v65, v241, v65, vcc
	s_branch .Lm2_qk
; template <int MODE  > ...
;     ...
;             if (ptype == 1) {
;                 const float thr = 0.5f * slope2 - mest;
; #pragma unroll
;                 for (int i = 0; i < 16; ++i) { s0[i] = (s0[i] < thr) ? s0[i] : -1e30f; s1[i] = (s1[i] < thr) ? s1[i] : -1e30f; }
.Lm2_edge1:
	v_sub_f32_e32 v253, v189, v1
	v_cmp_lt_f32_e32 vcc, v34, v253
	s_nop 1
	v_cndmask_b32_e32 v34, v241, v34, vcc
	v_cmp_lt_f32_e32 vcc, v35, v253
	s_nop 1
	v_cndmask_b32_e32 v35, v241, v35, vcc
	v_cmp_lt_f32_e32 vcc, v36, v253
	s_nop 1
	v_cndmask_b32_e32 v36, v241, v36, vcc
	v_cmp_lt_f32_e32 vcc, v37, v253
	s_nop 1
	v_cndmask_b32_e32 v37, v241, v37, vcc
	v_cmp_lt_f32_e32 vcc, v38, v253
	s_nop 1
	v_cndmask_b32_e32 v38, v241, v38, vcc
	v_cmp_lt_f32_e32 vcc, v39, v253
	s_nop 1
	v_cndmask_b32_e32 v39, v241, v39, vcc
	v_cmp_lt_f32_e32 vcc, v40, v253
	s_nop 1
	v_cndmask_b32_e32 v40, v241, v40, vcc
	v_cmp_lt_f32_e32 vcc, v41, v253
	s_nop 1
	v_cndmask_b32_e32 v41, v241, v41, vcc
	v_cmp_lt_f32_e32 vcc, v42, v253
	s_nop 1
	v_cndmask_b32_e32 v42, v241, v42, vcc
	v_cmp_lt_f32_e32 vcc, v43, v253
	s_nop 1
	v_cndmask_b32_e32 v43, v241, v43, vcc
	v_cmp_lt_f32_e32 vcc, v44, v253
	s_nop 1
	v_cndmask_b32_e32 v44, v241, v44, vcc
	v_cmp_lt_f32_e32 vcc, v45, v253
	s_nop 1
	v_cndmask_b32_e32 v45, v241, v45, vcc
	v_cmp_lt_f32_e32 vcc, v46, v253
	s_nop 1
	v_cndmask_b32_e32 v46, v241, v46, vcc
	v_cmp_lt_f32_e32 vcc, v47, v253
	s_nop 1
	v_cndmask_b32_e32 v47, v241, v47, vcc
	v_cmp_lt_f32_e32 vcc, v48, v253
	s_nop 1
	v_cndmask_b32_e32 v48, v241, v48, vcc
	v_cmp_lt_f32_e32 vcc, v49, v253
	s_nop 1
	v_cndmask_b32_e32 v49, v241, v49, vcc
	v_cmp_lt_f32_e32 vcc, v50, v253
	s_nop 1
	v_cndmask_b32_e32 v50, v241, v50, vcc
	v_cmp_lt_f32_e32 vcc, v51, v253
	s_nop 1
	v_cndmask_b32_e32 v51, v241, v51, vcc
	v_cmp_lt_f32_e32 vcc, v52, v253
	s_nop 1
	v_cndmask_b32_e32 v52, v241, v52, vcc
	v_cmp_lt_f32_e32 vcc, v53, v253
	s_nop 1
	v_cndmask_b32_e32 v53, v241, v53, vcc
	v_cmp_lt_f32_e32 vcc, v54, v253
	s_nop 1
	v_cndmask_b32_e32 v54, v241, v54, vcc
	v_cmp_lt_f32_e32 vcc, v55, v253
	s_nop 1
	v_cndmask_b32_e32 v55, v241, v55, vcc
	v_cmp_lt_f32_e32 vcc, v56, v253
	s_nop 1
	v_cndmask_b32_e32 v56, v241, v56, vcc
	v_cmp_lt_f32_e32 vcc, v57, v253
	s_nop 1
	v_cndmask_b32_e32 v57, v241, v57, vcc
	v_cmp_lt_f32_e32 vcc, v58, v253
	s_nop 1
	v_cndmask_b32_e32 v58, v241, v58, vcc
	v_cmp_lt_f32_e32 vcc, v59, v253
	s_nop 1
	v_cndmask_b32_e32 v59, v241, v59, vcc
	v_cmp_lt_f32_e32 vcc, v60, v253
	s_nop 1
	v_cndmask_b32_e32 v60, v241, v60, vcc
	v_cmp_lt_f32_e32 vcc, v61, v253
	s_nop 1
	v_cndmask_b32_e32 v61, v241, v61, vcc
	v_cmp_lt_f32_e32 vcc, v62, v253
	s_nop 1
	v_cndmask_b32_e32 v62, v241, v62, vcc
	v_cmp_lt_f32_e32 vcc, v63, v253
	s_nop 1
	v_cndmask_b32_e32 v63, v241, v63, vcc
	v_cmp_lt_f32_e32 vcc, v64, v253
	s_nop 1
	v_cndmask_b32_e32 v64, v241, v64, vcc
	v_cmp_lt_f32_e32 vcc, v65, v253
	s_nop 1
	v_cndmask_b32_e32 v65, v241, v65, vcc
; template <int MODE  > ...
;     ...
;             for (int kk = 0; kk < 4; ++kk) {
;                 const bf16x8 k0 = *(const LAS bf16x8*)(kb + col * KPITCH + kk * 16 + h * 8);
;                 const bf16x8 k1 = *(const LAS bf16x8*)(kb + (32 + col) * KPITCH + kk * 16 + h * 8);
;                 s0 = __builtin_amdgcn_mfma_f32_32x32x16_bf16(k0, qf[kk], s0, 0, 0, 0);
;                 s1 = __builtin_amdgcn_mfma_f32_32x32x16_bf16(k1, qf[kk], s1, 0, 0, 0);
;             }
;             if (MODE != 3) {
;                 float mx = fmaxf(s0[0], s1[0]);
; #pragma unroll
;                 for (int i = 1; i < 16; ++i) mx = fmaxf(mx, fmaxf(s0[i], s1[i]));
;                 mx = fmaxf(mx, shflx(mx, 32, lane));
;                 float alpha = 1.f;
;                 if (__builtin_amdgcn_ballot_w64(fresh || mx > 0.f) != 0ull) {
;                     const float moldr = fresh ? -1e29f : 0.f, mnewr = fmaxf(moldr, mx);
;                     alpha = __builtin_amdgcn_exp2f(moldr - mnewr);
;                     st.m = mest + mnewr;
; #pragma unroll
;                     for (int i = 0; i < 16; ++i) { s0[i] = __builtin_amdgcn_exp2f(s0[i] - mnewr); s1[i] = __builtin_amdgcn_exp2f(s1[i] - mnewr); }
;                     st.o0 *= alpha; st.o1 *= alpha;
;                 } else {
; #pragma unroll
;                     for (int i = 0; i < 16; ++i) { s0[i] = __builtin_amdgcn_exp2f(s0[i]); s1[i] = __builtin_amdgcn_exp2f(s1[i]); }
;                 }
;                 { typedef float f32x8 __attribute__((ext_vector_type(8)));
;                   const f32x16 t16 = s0 + s1;
;                   const f32x8 t8 = __builtin_shufflevector(t16, t16, 0, 1, 2, 3, 4, 5, 6, 7) + __builtin_shufflevector(t16, t16, 8, 9, 10, 11, 12, 13, 14, 15);
;                   const f32x4 t4 = __builtin_shufflevector(t8, t8, 0, 1, 2, 3) + __builtin_shufflevector(t8, t8, 4, 5, 6, 7);
;                   float ps = (t4[0] + t4[1]) + (t4[2] + t4[3]);
;                   ps += shflx(ps, 32, lane);
;                   st.l = st.l * alpha + ps; }
;                 bf16x8 pf[4];
; #pragma unroll
;                 for (int kk = 0; kk < 4; ++kk) {
;                     u32x4 pw;
;                     if (kk < 2) { pw.x = pk2(s0[8 * kk], s0[8 * kk + 1]); pw.y = pk2(s0[8 * kk + 2], s0[8 * kk + 3]); pw.z = pk2(s0[8 * kk + 4], s0[8 * kk + 5]); pw.w = pk2(s0[8 * kk + 6], s0[8 * kk + 7]); }
.Lm2_qk:
	s_waitcnt lgkmcnt(7)
	v_mfma_f32_32x32x16_bf16 v[34:49], v[66:69], v[144:147], v[34:49]
	s_waitcnt lgkmcnt(6)
	v_mfma_f32_32x32x16_bf16 v[50:65], v[70:73], v[144:147], v[50:65]
	s_waitcnt lgkmcnt(5)
	v_mfma_f32_32x32x16_bf16 v[34:49], v[74:77], v[148:151], v[34:49]
	s_waitcnt lgkmcnt(4)
	v_mfma_f32_32x32x16_bf16 v[50:65], v[78:81], v[148:151], v[50:65]
	s_waitcnt lgkmcnt(3)
	v_mfma_f32_32x32x16_bf16 v[34:49], v[82:85], v[152:155], v[34:49]
	s_waitcnt lgkmcnt(2)
	v_mfma_f32_32x32x16_bf16 v[50:65], v[86:89], v[152:155], v[50:65]
	s_waitcnt lgkmcnt(1)
	v_mfma_f32_32x32x16_bf16 v[34:49], v[90:93], v[156:159], v[34:49]
	s_waitcnt lgkmcnt(0)
	v_mfma_f32_32x32x16_bf16 v[50:65], v[94:97], v[156:159], v[50:65]
	ds_read_b64_tr_b16 v[66:67], v225 offset:18432
	ds_read_b64_tr_b16 v[68:69], v225 offset:19968
	ds_read_b64_tr_b16 v[70:71], v225 offset:18496
	ds_read_b64_tr_b16 v[72:73], v225 offset:20032
	ds_read_b64_tr_b16 v[74:75], v225 offset:21504
	ds_read_b64_tr_b16 v[76:77], v225 offset:23040
	ds_read_b64_tr_b16 v[78:79], v225 offset:21568
	ds_read_b64_tr_b16 v[80:81], v225 offset:23104
	s_nop 3
	v_max3_f32 v234, v34, v35, v36
	v_max3_f32 v234, v234, v37, v38
	v_max3_f32 v234, v234, v39, v40
	v_max3_f32 v234, v234, v41, v42
	v_max3_f32 v234, v234, v43, v44
	v_max3_f32 v234, v234, v45, v46
	v_max3_f32 v234, v234, v47, v48
	v_max3_f32 v235, v50, v51, v52
	v_max3_f32 v235, v235, v53, v54
	v_max3_f32 v235, v235, v55, v56
	v_max3_f32 v235, v235, v57, v58
	v_max3_f32 v235, v235, v59, v60
	v_max3_f32 v235, v235, v61, v62
	v_max3_f32 v235, v235, v63, v64
	v_max3_f32 v234, v234, v49, v65
	v_max_f32_e32 v234, v234, v235
	ds_bpermute_b32 v235, v164, v234
	ds_read_b64_tr_b16 v[82:83], v225 offset:24576
	ds_read_b64_tr_b16 v[84:85], v225 offset:26112
	ds_read_b64_tr_b16 v[86:87], v225 offset:24640
	ds_read_b64_tr_b16 v[88:89], v225 offset:26176
	ds_read_b64_tr_b16 v[90:91], v225 offset:27648
	ds_read_b64_tr_b16 v[92:93], v225 offset:29184
	ds_read_b64_tr_b16 v[94:95], v225 offset:27712
	ds_read_b64_tr_b16 v[96:97], v225 offset:29248
	s_waitcnt lgkmcnt(8)
	v_max_f32_e32 v234, v234, v235
	v_cmp_lt_f32_e32 vcc, 0, v234
	s_or_b64 vcc, s[14:15], vcc
	s_cbranch_vccz .Lm2_norescale
	v_cndmask_b32_e64 v235, 0, v242, s[14:15]
	v_max_f32_e32 v234, v235, v234
	v_sub_f32_e32 v235, v235, v234
	v_exp_f32_e32 v160, v235
	v_add_f32_e32 v192, v1, v234
	v_sub_f32_e32 v114, v34, v234
	v_exp_f32_e32 v114, v114
	v_sub_f32_e32 v98, v50, v234
	v_exp_f32_e32 v98, v98
	v_sub_f32_e32 v115, v35, v234
	v_exp_f32_e32 v115, v115
	v_sub_f32_e32 v99, v51, v234
	v_exp_f32_e32 v99, v99
	v_sub_f32_e32 v116, v36, v234
	v_exp_f32_e32 v116, v116
	v_sub_f32_e32 v100, v52, v234
	v_exp_f32_e32 v100, v100
	v_sub_f32_e32 v117, v37, v234
	v_exp_f32_e32 v117, v117
	v_sub_f32_e32 v101, v53, v234
	v_exp_f32_e32 v101, v101
	v_sub_f32_e32 v118, v38, v234
	v_exp_f32_e32 v118, v118
	v_sub_f32_e32 v102, v54, v234
	v_exp_f32_e32 v102, v102
	v_sub_f32_e32 v119, v39, v234
	v_exp_f32_e32 v119, v119
	v_sub_f32_e32 v103, v55, v234
	v_exp_f32_e32 v103, v103
	v_sub_f32_e32 v120, v40, v234
	v_exp_f32_e32 v120, v120
	v_sub_f32_e32 v104, v56, v234
	v_exp_f32_e32 v104, v104
	v_sub_f32_e32 v121, v41, v234
	v_exp_f32_e32 v121, v121
	v_sub_f32_e32 v105, v57, v234
	v_exp_f32_e32 v105, v105
	v_sub_f32_e32 v122, v42, v234
	v_exp_f32_e32 v122, v122
	v_sub_f32_e32 v106, v58, v234
	v_exp_f32_e32 v106, v106
	v_sub_f32_e32 v123, v43, v234
	v_exp_f32_e32 v123, v123
	v_sub_f32_e32 v107, v59, v234
	v_exp_f32_e32 v107, v107
	v_sub_f32_e32 v124, v44, v234
	v_exp_f32_e32 v124, v124
	v_sub_f32_e32 v108, v60, v234
	v_exp_f32_e32 v108, v108
	v_sub_f32_e32 v125, v45, v234
	v_exp_f32_e32 v125, v125
	v_sub_f32_e32 v109, v61, v234
	v_exp_f32_e32 v109, v109
	v_sub_f32_e32 v126, v46, v234
	v_exp_f32_e32 v126, v126
	v_sub_f32_e32 v110, v62, v234
	v_exp_f32_e32 v110, v110
	v_sub_f32_e32 v127, v47, v234
	v_exp_f32_e32 v127, v127
	v_sub_f32_e32 v111, v63, v234
	v_exp_f32_e32 v111, v111
	v_sub_f32_e32 v128, v48, v234
	v_exp_f32_e32 v128, v128
	v_sub_f32_e32 v112, v64, v234
	v_exp_f32_e32 v112, v112
	v_sub_f32_e32 v129, v49, v234
	v_exp_f32_e32 v129, v129
	v_sub_f32_e32 v113, v65, v234
	v_exp_f32_e32 v113, v113
	v_pk_mul_f32 v[18:19], v[18:19], v[160:161] op_sel_hi:[1,0]
	v_pk_mul_f32 v[20:21], v[20:21], v[160:161] op_sel_hi:[1,0]
	v_pk_mul_f32 v[22:23], v[22:23], v[160:161] op_sel_hi:[1,0]
	v_pk_mul_f32 v[24:25], v[24:25], v[160:161] op_sel_hi:[1,0]
	v_pk_mul_f32 v[26:27], v[26:27], v[160:161] op_sel_hi:[1,0]
	v_pk_mul_f32 v[28:29], v[28:29], v[160:161] op_sel_hi:[1,0]
	v_pk_mul_f32 v[30:31], v[30:31], v[160:161] op_sel_hi:[1,0]
	v_pk_mul_f32 v[32:33], v[32:33], v[160:161] op_sel_hi:[1,0]
	v_pk_mul_f32 v[2:3], v[2:3], v[160:161] op_sel_hi:[1,0]
	v_pk_mul_f32 v[4:5], v[4:5], v[160:161] op_sel_hi:[1,0]
	v_pk_mul_f32 v[6:7], v[6:7], v[160:161] op_sel_hi:[1,0]
	v_pk_mul_f32 v[8:9], v[8:9], v[160:161] op_sel_hi:[1,0]
	v_pk_mul_f32 v[10:11], v[10:11], v[160:161] op_sel_hi:[1,0]
	v_pk_mul_f32 v[12:13], v[12:13], v[160:161] op_sel_hi:[1,0]
	v_pk_mul_f32 v[14:15], v[14:15], v[160:161] op_sel_hi:[1,0]
	v_pk_mul_f32 v[16:17], v[16:17], v[160:161] op_sel_hi:[1,0]
	s_branch .Lm2_pv

; __device__ __forceinline__ void attn_unit(unsigned char* ws, LAS unsigned char* lds, int b, int g, int c, const int tid) {
;     ...
;     { const float gate2 = ((const float*)(ws + WS_G))[row * 32 + head * 3 + 2]; const float sc = st.l > 0.f ? gate2 / st.l : 0.f;
; #pragma unroll
;       for (int i = 0; i < 16; ++i) { st.o0[i] = outl[i * 512] + st.o0[i] * sc; st.o1[i] = outl[(16 + i) * 512] + st.o1[i] * sc; } }
.LBB0_285:
	v_mov_b32_e32 v34, 0
	v_cmp_lt_f32_e32 vcc, 0, v35
	s_and_saveexec_b64 s[4:5], vcc
	s_cbranch_execz .LBB0_131
	v_mov_b32_e32 v1, v247
	s_waitcnt vmcnt(0) lgkmcnt(0)
	v_div_scale_f32 v34, s[14:15], v35, v35, v1
	v_rcp_f32_e32 v36, v34
	v_div_scale_f32 v37, vcc, v1, v35, v1
	v_fma_f32 v38, -v34, v36, 1.0
	v_fmac_f32_e32 v36, v38, v36
	v_mul_f32_e32 v38, v37, v36
	v_fma_f32 v39, -v34, v38, v37
	v_fmac_f32_e32 v38, v39, v36
	v_fma_f32 v34, -v34, v38, v37
	v_div_fmas_f32 v34, v34, v36, v38
	v_div_fixup_f32 v34, v34, v35, v1
	s_branch .LBB0_131
